# GEMM phase bodies: duplicate per-tile accumulator clear removed from the hot path (kept on the zero-trip path), remaining clear uses 64-bit moves; plus earlier epilogue and attention changes; numerics
# speedup vs baseline: 1.0312x; 1.0027x over previous
; template <class Epi> __device__ __forceinline__ void gemm_phase(LAS unsigned char* lds, const Gemm g, const StaticOrder& S, const Epi& E, const int tid) {
;     ...
;         const bool has_next = S.next(ui + 1, nxt);
;         const char* nA = has_next ? (const char*)g.A + (size_t)nxt.pm * tstepA + (size_t)(nxt.pn & g.amask) * g.astride : cA; const char* nB = has_next ? (const char*)g.Bt + (size_t)nxt.pn * tstepB : cB;
;     ...
; #pragma unroll
;         for (int a = 0; a < 2; ++a)
; #pragma unroll
;             for (int b = 0; b < 2; ++b)
; #pragma unroll
;                 for (int m = 0; m < 4; ++m)
; #pragma unroll
;                     for (int n = 0; n < 2; ++n) acc[a][b][m][n] = (f32x4){0.f, 0.f, 0.f, 0.f};
.LBB0_189:
	s_ashr_i32 s43, s42, 31
	s_lshl_b64 s[22:23], s[42:43], 17
	s_add_u32 s44, s34, s22
	s_addc_u32 s45, s35, s23
	s_ashr_i32 s17, s16, 31
	s_lshl_b64 s[22:23], s[16:17], 17
	s_add_u32 s48, s38, s22
	s_addc_u32 s49, s39, s23
	s_andn2_b64 vcc, exec, s[12:13]
	s_cbranch_vccnz .Lacc_clear_0
	s_and_b64 s[22:23], s[40:41], exec
	s_cselect_b32 s17, s45, s21
	s_cselect_b32 s43, s44, s20
	s_cselect_b32 s77, s49, s19
	s_cselect_b32 s88, s48, s18
	s_add_u32 s26, s20, 0x100
	s_addc_u32 s27, s21, 0
	s_add_u32 s89, s18, 0x100
	v_mov_b64_e32 v[2:3], 0
	v_mov_b64_e32 v[4:5], 0
	v_mov_b64_e32 v[6:7], 0
	v_mov_b64_e32 v[8:9], 0
	v_mov_b64_e32 v[10:11], 0
	v_mov_b64_e32 v[12:13], 0
	v_mov_b64_e32 v[14:15], 0
	v_mov_b64_e32 v[16:17], 0
	v_mov_b64_e32 v[18:19], 0
	v_mov_b64_e32 v[20:21], 0
	v_mov_b64_e32 v[22:23], 0
	v_mov_b64_e32 v[24:25], 0
	v_mov_b64_e32 v[26:27], 0
	v_mov_b64_e32 v[28:29], 0
	v_mov_b64_e32 v[30:31], 0
	v_mov_b64_e32 v[32:33], 0
	v_mov_b64_e32 v[34:35], 0
	v_mov_b64_e32 v[36:37], 0
	v_mov_b64_e32 v[38:39], 0
	v_mov_b64_e32 v[40:41], 0
	v_mov_b64_e32 v[42:43], 0
	v_mov_b64_e32 v[44:45], 0
	v_mov_b64_e32 v[46:47], 0
	v_mov_b64_e32 v[48:49], 0
	v_mov_b64_e32 v[50:51], 0
	v_mov_b64_e32 v[52:53], 0
	v_mov_b64_e32 v[54:55], 0
	v_mov_b64_e32 v[56:57], 0
	v_mov_b64_e32 v[58:59], 0
	v_mov_b64_e32 v[60:61], 0
	v_mov_b64_e32 v[62:63], 0
	v_mov_b64_e32 v[64:65], 0
	v_mov_b64_e32 v[66:67], 0
	v_mov_b64_e32 v[68:69], 0
	v_mov_b64_e32 v[70:71], 0
	v_mov_b64_e32 v[72:73], 0
	v_mov_b64_e32 v[74:75], 0
	v_mov_b64_e32 v[76:77], 0
	v_mov_b64_e32 v[78:79], 0
	v_mov_b64_e32 v[80:81], 0
	v_mov_b64_e32 v[82:83], 0
	v_mov_b64_e32 v[84:85], 0
	v_mov_b64_e32 v[86:87], 0
	v_mov_b64_e32 v[88:89], 0
	v_mov_b64_e32 v[90:91], 0
	v_mov_b64_e32 v[92:93], 0
	v_mov_b64_e32 v[94:95], 0
	v_mov_b64_e32 v[96:97], 0
	v_mov_b64_e32 v[98:99], 0
	v_mov_b64_e32 v[100:101], 0
	v_mov_b64_e32 v[102:103], 0
	v_mov_b64_e32 v[104:105], 0
	v_mov_b64_e32 v[106:107], 0
	v_mov_b64_e32 v[108:109], 0
	v_mov_b64_e32 v[110:111], 0
	v_mov_b64_e32 v[112:113], 0
	v_mov_b64_e32 v[114:115], 0
	v_mov_b64_e32 v[116:117], 0
	v_mov_b64_e32 v[118:119], 0
	v_mov_b64_e32 v[120:121], 0
	v_mov_b64_e32 v[122:123], 0
	v_mov_b64_e32 v[124:125], 0
	v_mov_b64_e32 v[126:127], 0
	v_mov_b64_e32 v[128:129], 0
	s_addc_u32 s90, s19, 0
	s_mov_b32 s18, 0

; template <class Epi> __device__ __forceinline__ void gemm_phase(LAS unsigned char* lds, const Gemm g, const StaticOrder& S, const Epi& E, const int tid) {
;     ...
; #pragma unroll
;         for (int a = 0; a < 2; ++a)
; #pragma unroll
;             for (int b = 0; b < 2; ++b)
; #pragma unroll
;                 for (int m = 0; m < 4; ++m)
; #pragma unroll
;                     for (int n = 0; n < 2; ++n) acc[a][b][m][n] = (f32x4){0.f, 0.f, 0.f, 0.f};
.Lacc_clear_0:
	v_mov_b32_e32 v125, 0
	v_mov_b32_e32 v124, v125
	v_mov_b32_e32 v123, v125
	v_mov_b32_e32 v122, v125
	v_mov_b32_e32 v129, v125
	v_mov_b32_e32 v128, v125
	v_mov_b32_e32 v127, v125
	v_mov_b32_e32 v126, v125
	v_mov_b32_e32 v113, v125
	v_mov_b32_e32 v112, v125
	v_mov_b32_e32 v111, v125
	v_mov_b32_e32 v110, v125
	v_mov_b32_e32 v109, v125
	v_mov_b32_e32 v108, v125
	v_mov_b32_e32 v107, v125
	v_mov_b32_e32 v106, v125
	v_mov_b32_e32 v97, v125
	v_mov_b32_e32 v96, v125
	v_mov_b32_e32 v95, v125
	v_mov_b32_e32 v94, v125
	v_mov_b32_e32 v93, v125
	v_mov_b32_e32 v92, v125
	v_mov_b32_e32 v91, v125
	v_mov_b32_e32 v90, v125
	v_mov_b32_e32 v81, v125
	v_mov_b32_e32 v80, v125
	v_mov_b32_e32 v79, v125
	v_mov_b32_e32 v78, v125
	v_mov_b32_e32 v77, v125
	v_mov_b32_e32 v76, v125
	v_mov_b32_e32 v75, v125
	v_mov_b32_e32 v74, v125
	v_mov_b32_e32 v121, v125
	v_mov_b32_e32 v120, v125
	v_mov_b32_e32 v119, v125
	v_mov_b32_e32 v118, v125
	v_mov_b32_e32 v117, v125
	v_mov_b32_e32 v116, v125
	v_mov_b32_e32 v115, v125
	v_mov_b32_e32 v114, v125
	v_mov_b32_e32 v105, v125
	v_mov_b32_e32 v104, v125
	v_mov_b32_e32 v103, v125
	v_mov_b32_e32 v102, v125
	v_mov_b32_e32 v101, v125
	v_mov_b32_e32 v100, v125
	v_mov_b32_e32 v99, v125
	v_mov_b32_e32 v98, v125
	v_mov_b32_e32 v89, v125
	v_mov_b32_e32 v88, v125
	v_mov_b32_e32 v87, v125
	v_mov_b32_e32 v86, v125
	v_mov_b32_e32 v85, v125
	v_mov_b32_e32 v84, v125
	v_mov_b32_e32 v83, v125
	v_mov_b32_e32 v82, v125
	v_mov_b32_e32 v73, v125
	v_mov_b32_e32 v72, v125
	v_mov_b32_e32 v71, v125
	v_mov_b32_e32 v70, v125
	v_mov_b32_e32 v69, v125
	v_mov_b32_e32 v68, v125
	v_mov_b32_e32 v67, v125
	v_mov_b32_e32 v66, v125
	v_mov_b32_e32 v65, v125
	v_mov_b32_e32 v64, v125
	v_mov_b32_e32 v63, v125
	v_mov_b32_e32 v62, v125
	v_mov_b32_e32 v61, v125
	v_mov_b32_e32 v60, v125
	v_mov_b32_e32 v59, v125
	v_mov_b32_e32 v58, v125
	v_mov_b32_e32 v49, v125
	v_mov_b32_e32 v48, v125
	v_mov_b32_e32 v47, v125
	v_mov_b32_e32 v46, v125
	v_mov_b32_e32 v45, v125
	v_mov_b32_e32 v44, v125
	v_mov_b32_e32 v43, v125
	v_mov_b32_e32 v42, v125
	v_mov_b32_e32 v33, v125
	v_mov_b32_e32 v32, v125
	v_mov_b32_e32 v31, v125
	v_mov_b32_e32 v30, v125
	v_mov_b32_e32 v29, v125
	v_mov_b32_e32 v28, v125
	v_mov_b32_e32 v27, v125
	v_mov_b32_e32 v26, v125
	v_mov_b32_e32 v17, v125
	v_mov_b32_e32 v16, v125
	v_mov_b32_e32 v15, v125
	v_mov_b32_e32 v14, v125
	v_mov_b32_e32 v13, v125
	v_mov_b32_e32 v12, v125
	v_mov_b32_e32 v11, v125
	v_mov_b32_e32 v10, v125
	v_mov_b32_e32 v57, v125
	v_mov_b32_e32 v56, v125
	v_mov_b32_e32 v55, v125
	v_mov_b32_e32 v54, v125
	v_mov_b32_e32 v53, v125
	v_mov_b32_e32 v52, v125
	v_mov_b32_e32 v51, v125
	v_mov_b32_e32 v50, v125
	v_mov_b32_e32 v41, v125
	v_mov_b32_e32 v40, v125
	v_mov_b32_e32 v39, v125
	v_mov_b32_e32 v38, v125
	v_mov_b32_e32 v37, v125
	v_mov_b32_e32 v36, v125
	v_mov_b32_e32 v35, v125
	v_mov_b32_e32 v34, v125
	v_mov_b32_e32 v25, v125
	v_mov_b32_e32 v24, v125
	v_mov_b32_e32 v23, v125
	v_mov_b32_e32 v22, v125
	v_mov_b32_e32 v21, v125
	v_mov_b32_e32 v20, v125
	v_mov_b32_e32 v19, v125
	v_mov_b32_e32 v18, v125
	v_mov_b32_e32 v9, v125
	v_mov_b32_e32 v8, v125
	v_mov_b32_e32 v7, v125
	v_mov_b32_e32 v6, v125
	v_mov_b32_e32 v5, v125
	v_mov_b32_e32 v4, v125
	v_mov_b32_e32 v3, v125
	v_mov_b32_e32 v2, v125
	s_branch .LBB0_192

; template <class Epi> __device__ __forceinline__ void gemm_phase(LAS unsigned char* lds, const Gemm g, const StaticOrder& S, const Epi& E, const int tid) {
;     ...
;         const char* nA = has_next ? (const char*)g.A + (size_t)nxt.pm * tstepA + (size_t)(nxt.pn & g.amask) * g.astride : cA; const char* nB = has_next ? (const char*)g.Bt + (size_t)nxt.pn * tstepB : cB;
;         for (int t = 0; t < nt; t += 2) {
;             const bool last = (t == nt - 2);
;             const char* a1 = cA + (size_t)(t + 1) * kstep;
;             const char* a2 = last ? nA : cA + (size_t)(t + 2) * kstep; const char* b2 = last ? nB : cB + (size_t)(t + 2) * kstep;
;     ...
; #pragma unroll
;         for (int a = 0; a < 2; ++a)
; #pragma unroll
;             for (int b = 0; b < 2; ++b)
; #pragma unroll
;                 for (int m = 0; m < 4; ++m)
; #pragma unroll
;                     for (int n = 0; n < 2; ++n) acc[a][b][m][n] = (f32x4){0.f, 0.f, 0.f, 0.f};
.LBB0_216:
	s_ashr_i32 s97, s96, 31
	s_lshl_b64 s[4:5], s[96:97], 19
	s_add_u32 s4, s42, s4
	s_addc_u32 s5, s43, s5
	s_lshl_b32 s6, s94, 8
	s_and_b32 s6, s6, 0x700
	s_add_u32 s4, s4, s6
	s_addc_u32 s5, s5, 0
	s_ashr_i32 s95, s94, 31
	s_lshl_b64 s[6:7], s[94:95], 16
	s_add_u32 s6, s14, s6
	s_addc_u32 s7, s15, s7
	s_andn2_b64 vcc, exec, s[90:91]
	s_cbranch_vccnz .Lacc_clear_1
	s_and_b64 s[12:13], s[40:41], exec
	s_cselect_b32 s46, s5, s11
	s_cselect_b32 s47, s4, s10
	s_cselect_b32 s76, s7, s9
	s_cselect_b32 s77, s6, s8
	s_add_u32 s26, s10, 0x100
	s_addc_u32 s27, s11, 0
	s_add_u32 s81, s8, 0x100
	v_mov_b64_e32 v[2:3], 0
	v_mov_b64_e32 v[4:5], 0
	v_mov_b64_e32 v[6:7], 0
	v_mov_b64_e32 v[8:9], 0
	v_mov_b64_e32 v[10:11], 0
	v_mov_b64_e32 v[12:13], 0
	v_mov_b64_e32 v[14:15], 0
	v_mov_b64_e32 v[16:17], 0
	v_mov_b64_e32 v[18:19], 0
	v_mov_b64_e32 v[20:21], 0
	v_mov_b64_e32 v[22:23], 0
	v_mov_b64_e32 v[24:25], 0
	v_mov_b64_e32 v[26:27], 0
	v_mov_b64_e32 v[28:29], 0
	v_mov_b64_e32 v[30:31], 0
	v_mov_b64_e32 v[32:33], 0
	v_mov_b64_e32 v[34:35], 0
	v_mov_b64_e32 v[36:37], 0
	v_mov_b64_e32 v[38:39], 0
	v_mov_b64_e32 v[40:41], 0
	v_mov_b64_e32 v[42:43], 0
	v_mov_b64_e32 v[44:45], 0
	v_mov_b64_e32 v[46:47], 0
	v_mov_b64_e32 v[48:49], 0
	v_mov_b64_e32 v[50:51], 0
	v_mov_b64_e32 v[52:53], 0
	v_mov_b64_e32 v[54:55], 0
	v_mov_b64_e32 v[56:57], 0
	v_mov_b64_e32 v[58:59], 0
	v_mov_b64_e32 v[60:61], 0
	v_mov_b64_e32 v[62:63], 0
	v_mov_b64_e32 v[64:65], 0
	v_mov_b64_e32 v[66:67], 0
	v_mov_b64_e32 v[68:69], 0
	v_mov_b64_e32 v[70:71], 0
	v_mov_b64_e32 v[72:73], 0
	v_mov_b64_e32 v[74:75], 0
	v_mov_b64_e32 v[76:77], 0
	v_mov_b64_e32 v[78:79], 0
	v_mov_b64_e32 v[80:81], 0
	v_mov_b64_e32 v[86:87], 0
	v_mov_b64_e32 v[88:89], 0
	v_mov_b64_e32 v[90:91], 0
	v_mov_b64_e32 v[92:93], 0
	v_mov_b64_e32 v[110:111], 0
	v_mov_b64_e32 v[112:113], 0
	v_mov_b64_e32 v[114:115], 0
	v_mov_b64_e32 v[116:117], 0
	v_mov_b64_e32 v[122:123], 0
	v_mov_b64_e32 v[124:125], 0
	v_mov_b64_e32 v[126:127], 0
	v_mov_b64_e32 v[128:129], 0
	v_mov_b64_e32 v[130:131], 0
	v_mov_b64_e32 v[132:133], 0
	v_mov_b64_e32 v[134:135], 0
	v_mov_b64_e32 v[136:137], 0
	v_mov_b64_e32 v[142:143], 0
	v_mov_b64_e32 v[144:145], 0
	v_mov_b64_e32 v[146:147], 0
	v_mov_b64_e32 v[148:149], 0
	v_mov_b64_e32 v[150:151], 0
	v_mov_b64_e32 v[152:153], 0
	v_mov_b64_e32 v[154:155], 0
	v_mov_b64_e32 v[156:157], 0
	s_addc_u32 s84, s9, 0
	s_mov_b32 s8, 0

; template <class Epi> __device__ __forceinline__ void gemm_phase(LAS unsigned char* lds, const Gemm g, const StaticOrder& S, const Epi& E, const int tid) {
;     ...
; #pragma unroll
;         for (int a = 0; a < 2; ++a)
; #pragma unroll
;             for (int b = 0; b < 2; ++b)
; #pragma unroll
;                 for (int m = 0; m < 4; ++m)
; #pragma unroll
;                     for (int n = 0; n < 2; ++n) acc[a][b][m][n] = (f32x4){0.f, 0.f, 0.f, 0.f};
.Lacc_clear_1:
	v_mov_b32_e32 v157, 0
	v_mov_b32_e32 v156, v157
	v_mov_b32_e32 v155, v157
	v_mov_b32_e32 v154, v157
	v_mov_b32_e32 v149, v157
	v_mov_b32_e32 v148, v157
	v_mov_b32_e32 v147, v157
	v_mov_b32_e32 v146, v157
	v_mov_b32_e32 v137, v157
	v_mov_b32_e32 v136, v157
	v_mov_b32_e32 v135, v157
	v_mov_b32_e32 v134, v157
	v_mov_b32_e32 v129, v157
	v_mov_b32_e32 v128, v157
	v_mov_b32_e32 v127, v157
	v_mov_b32_e32 v126, v157
	v_mov_b32_e32 v117, v157
	v_mov_b32_e32 v116, v157
	v_mov_b32_e32 v115, v157
	v_mov_b32_e32 v114, v157
	v_mov_b32_e32 v93, v157
	v_mov_b32_e32 v92, v157
	v_mov_b32_e32 v91, v157
	v_mov_b32_e32 v90, v157
	v_mov_b32_e32 v81, v157
	v_mov_b32_e32 v80, v157
	v_mov_b32_e32 v79, v157
	v_mov_b32_e32 v78, v157
	v_mov_b32_e32 v73, v157
	v_mov_b32_e32 v72, v157
	v_mov_b32_e32 v71, v157
	v_mov_b32_e32 v70, v157
	v_mov_b32_e32 v153, v157
	v_mov_b32_e32 v152, v157
	v_mov_b32_e32 v151, v157
	v_mov_b32_e32 v150, v157
	v_mov_b32_e32 v145, v157
	v_mov_b32_e32 v144, v157
	v_mov_b32_e32 v143, v157
	v_mov_b32_e32 v142, v157
	v_mov_b32_e32 v133, v157
	v_mov_b32_e32 v132, v157
	v_mov_b32_e32 v131, v157
	v_mov_b32_e32 v130, v157
	v_mov_b32_e32 v125, v157
	v_mov_b32_e32 v124, v157
	v_mov_b32_e32 v123, v157
	v_mov_b32_e32 v122, v157
	v_mov_b32_e32 v113, v157
	v_mov_b32_e32 v112, v157
	v_mov_b32_e32 v111, v157
	v_mov_b32_e32 v110, v157
	v_mov_b32_e32 v89, v157
	v_mov_b32_e32 v88, v157
	v_mov_b32_e32 v87, v157
	v_mov_b32_e32 v86, v157
	v_mov_b32_e32 v77, v157
	v_mov_b32_e32 v76, v157
	v_mov_b32_e32 v75, v157
	v_mov_b32_e32 v74, v157
	v_mov_b32_e32 v69, v157
	v_mov_b32_e32 v68, v157
	v_mov_b32_e32 v67, v157
	v_mov_b32_e32 v66, v157
	v_mov_b32_e32 v65, v157
	v_mov_b32_e32 v64, v157
	v_mov_b32_e32 v63, v157
	v_mov_b32_e32 v62, v157
	v_mov_b32_e32 v57, v157
	v_mov_b32_e32 v56, v157
	v_mov_b32_e32 v55, v157
	v_mov_b32_e32 v54, v157
	v_mov_b32_e32 v49, v157
	v_mov_b32_e32 v48, v157
	v_mov_b32_e32 v47, v157
	v_mov_b32_e32 v46, v157
	v_mov_b32_e32 v41, v157
	v_mov_b32_e32 v40, v157
	v_mov_b32_e32 v39, v157
	v_mov_b32_e32 v38, v157
	v_mov_b32_e32 v33, v157
	v_mov_b32_e32 v32, v157
	v_mov_b32_e32 v31, v157
	v_mov_b32_e32 v30, v157
	v_mov_b32_e32 v25, v157
	v_mov_b32_e32 v24, v157
	v_mov_b32_e32 v23, v157
	v_mov_b32_e32 v22, v157
	v_mov_b32_e32 v17, v157
	v_mov_b32_e32 v16, v157
	v_mov_b32_e32 v15, v157
	v_mov_b32_e32 v14, v157
	v_mov_b32_e32 v9, v157
	v_mov_b32_e32 v8, v157
	v_mov_b32_e32 v7, v157
	v_mov_b32_e32 v6, v157
	v_mov_b32_e32 v61, v157
	v_mov_b32_e32 v60, v157
	v_mov_b32_e32 v59, v157
	v_mov_b32_e32 v58, v157
	v_mov_b32_e32 v53, v157
	v_mov_b32_e32 v52, v157
	v_mov_b32_e32 v51, v157
	v_mov_b32_e32 v50, v157
	v_mov_b32_e32 v45, v157
	v_mov_b32_e32 v44, v157
	v_mov_b32_e32 v43, v157
	v_mov_b32_e32 v42, v157
	v_mov_b32_e32 v37, v157
	v_mov_b32_e32 v36, v157
	v_mov_b32_e32 v35, v157
	v_mov_b32_e32 v34, v157
	v_mov_b32_e32 v29, v157
	v_mov_b32_e32 v28, v157
	v_mov_b32_e32 v27, v157
	v_mov_b32_e32 v26, v157
	v_mov_b32_e32 v21, v157
	v_mov_b32_e32 v20, v157
	v_mov_b32_e32 v19, v157
	v_mov_b32_e32 v18, v157
	v_mov_b32_e32 v13, v157
	v_mov_b32_e32 v12, v157
	v_mov_b32_e32 v11, v157
	v_mov_b32_e32 v10, v157
	v_mov_b32_e32 v5, v157
	v_mov_b32_e32 v4, v157
	v_mov_b32_e32 v3, v157
	v_mov_b32_e32 v2, v157
	s_branch .LBB0_220

; template <class Epi> __device__ __forceinline__ void gemm_phase(LAS unsigned char* lds, const Gemm g, const StaticOrder& S, const Epi& E, const int tid) {
;     ...
;         const char* nA = has_next ? (const char*)g.A + (size_t)nxt.pm * tstepA + (size_t)(nxt.pn & g.amask) * g.astride : cA; const char* nB = has_next ? (const char*)g.Bt + (size_t)nxt.pn * tstepB : cB;
;         for (int t = 0; t < nt; t += 2) {
;             const bool last = (t == nt - 2);
;             const char* a1 = cA + (size_t)(t + 1) * kstep;
;             const char* a2 = last ? nA : cA + (size_t)(t + 2) * kstep; const char* b2 = last ? nB : cB + (size_t)(t + 2) * kstep;
;     ...
; #pragma unroll
;         for (int a = 0; a < 2; ++a)
; #pragma unroll
;             for (int b = 0; b < 2; ++b)
; #pragma unroll
;                 for (int m = 0; m < 4; ++m)
; #pragma unroll
;                     for (int n = 0; n < 2; ++n) acc[a][b][m][n] = (f32x4){0.f, 0.f, 0.f, 0.f};
.LBB0_238:
	s_ashr_i32 s93, s92, 31
	s_lshl_b64 s[8:9], s[92:93], 20
	s_add_u32 s94, s12, s8
	s_addc_u32 s95, s13, s9
	s_ashr_i32 s91, s90, 31
	s_lshl_b64 s[8:9], s[90:91], 20
	s_add_u32 s96, s14, s8
	s_addc_u32 s97, s15, s9
	s_andn2_b64 vcc, exec, s[86:87]
	s_cbranch_vccnz .Lacc_clear_2
	s_and_b64 s[8:9], s[40:41], exec
	s_cselect_b32 s11, s95, s7
	s_cselect_b32 s35, s94, s6
	s_cselect_b32 s36, s97, s5
	s_cselect_b32 s38, s96, s4
	s_add_u32 s26, s6, 0x100
	s_addc_u32 s27, s7, 0
	s_add_u32 s39, s4, 0x100
	v_mov_b64_e32 v[2:3], 0
	v_mov_b64_e32 v[4:5], 0
	v_mov_b64_e32 v[6:7], 0
	v_mov_b64_e32 v[8:9], 0
	v_mov_b64_e32 v[10:11], 0
	v_mov_b64_e32 v[12:13], 0
	v_mov_b64_e32 v[14:15], 0
	v_mov_b64_e32 v[16:17], 0
	v_mov_b64_e32 v[18:19], 0
	v_mov_b64_e32 v[20:21], 0
	v_mov_b64_e32 v[22:23], 0
	v_mov_b64_e32 v[24:25], 0
	v_mov_b64_e32 v[26:27], 0
	v_mov_b64_e32 v[28:29], 0
	v_mov_b64_e32 v[30:31], 0
	v_mov_b64_e32 v[32:33], 0
	v_mov_b64_e32 v[34:35], 0
	v_mov_b64_e32 v[36:37], 0
	v_mov_b64_e32 v[38:39], 0
	v_mov_b64_e32 v[40:41], 0
	v_mov_b64_e32 v[42:43], 0
	v_mov_b64_e32 v[44:45], 0
	v_mov_b64_e32 v[46:47], 0
	v_mov_b64_e32 v[48:49], 0
	v_mov_b64_e32 v[50:51], 0
	v_mov_b64_e32 v[52:53], 0
	v_mov_b64_e32 v[54:55], 0
	v_mov_b64_e32 v[56:57], 0
	v_mov_b64_e32 v[58:59], 0
	v_mov_b64_e32 v[60:61], 0
	v_mov_b64_e32 v[62:63], 0
	v_mov_b64_e32 v[64:65], 0
	v_mov_b64_e32 v[66:67], 0
	v_mov_b64_e32 v[68:69], 0
	v_mov_b64_e32 v[70:71], 0
	v_mov_b64_e32 v[72:73], 0
	v_mov_b64_e32 v[74:75], 0
	v_mov_b64_e32 v[76:77], 0
	v_mov_b64_e32 v[78:79], 0
	v_mov_b64_e32 v[80:81], 0
	v_mov_b64_e32 v[82:83], 0
	v_mov_b64_e32 v[84:85], 0
	v_mov_b64_e32 v[86:87], 0
	v_mov_b64_e32 v[88:89], 0
	v_mov_b64_e32 v[90:91], 0
	v_mov_b64_e32 v[92:93], 0
	v_mov_b64_e32 v[94:95], 0
	v_mov_b64_e32 v[96:97], 0
	v_mov_b64_e32 v[98:99], 0
	v_mov_b64_e32 v[100:101], 0
	v_mov_b64_e32 v[102:103], 0
	v_mov_b64_e32 v[104:105], 0
	v_mov_b64_e32 v[106:107], 0
	v_mov_b64_e32 v[108:109], 0
	v_mov_b64_e32 v[110:111], 0
	v_mov_b64_e32 v[112:113], 0
	v_mov_b64_e32 v[114:115], 0
	v_mov_b64_e32 v[116:117], 0
	v_mov_b64_e32 v[118:119], 0
	v_mov_b64_e32 v[120:121], 0
	v_mov_b64_e32 v[122:123], 0
	v_mov_b64_e32 v[124:125], 0
	v_mov_b64_e32 v[126:127], 0
	v_mov_b64_e32 v[128:129], 0
	s_addc_u32 s42, s5, 0
	s_mov_b32 s4, 0

; template <class Epi> __device__ __forceinline__ void gemm_phase(LAS unsigned char* lds, const Gemm g, const StaticOrder& S, const Epi& E, const int tid) {
;     ...
; #pragma unroll
;         for (int a = 0; a < 2; ++a)
; #pragma unroll
;             for (int b = 0; b < 2; ++b)
; #pragma unroll
;                 for (int m = 0; m < 4; ++m)
; #pragma unroll
;                     for (int n = 0; n < 2; ++n) acc[a][b][m][n] = (f32x4){0.f, 0.f, 0.f, 0.f};
.Lacc_clear_2:
	v_mov_b32_e32 v129, 0
	v_mov_b32_e32 v128, v129
	v_mov_b32_e32 v127, v129
	v_mov_b32_e32 v126, v129
	v_mov_b32_e32 v125, v129
	v_mov_b32_e32 v124, v129
	v_mov_b32_e32 v123, v129
	v_mov_b32_e32 v122, v129
	v_mov_b32_e32 v113, v129
	v_mov_b32_e32 v112, v129
	v_mov_b32_e32 v111, v129
	v_mov_b32_e32 v110, v129
	v_mov_b32_e32 v109, v129
	v_mov_b32_e32 v108, v129
	v_mov_b32_e32 v107, v129
	v_mov_b32_e32 v106, v129
	v_mov_b32_e32 v97, v129
	v_mov_b32_e32 v96, v129
	v_mov_b32_e32 v95, v129
	v_mov_b32_e32 v94, v129
	v_mov_b32_e32 v93, v129
	v_mov_b32_e32 v92, v129
	v_mov_b32_e32 v91, v129
	v_mov_b32_e32 v90, v129
	v_mov_b32_e32 v81, v129
	v_mov_b32_e32 v80, v129
	v_mov_b32_e32 v79, v129
	v_mov_b32_e32 v78, v129
	v_mov_b32_e32 v77, v129
	v_mov_b32_e32 v76, v129
	v_mov_b32_e32 v75, v129
	v_mov_b32_e32 v74, v129
	v_mov_b32_e32 v121, v129
	v_mov_b32_e32 v120, v129
	v_mov_b32_e32 v119, v129
	v_mov_b32_e32 v118, v129
	v_mov_b32_e32 v117, v129
	v_mov_b32_e32 v116, v129
	v_mov_b32_e32 v115, v129
	v_mov_b32_e32 v114, v129
	v_mov_b32_e32 v105, v129
	v_mov_b32_e32 v104, v129
	v_mov_b32_e32 v103, v129
	v_mov_b32_e32 v102, v129
	v_mov_b32_e32 v101, v129
	v_mov_b32_e32 v100, v129
	v_mov_b32_e32 v99, v129
	v_mov_b32_e32 v98, v129
	v_mov_b32_e32 v89, v129
	v_mov_b32_e32 v88, v129
	v_mov_b32_e32 v87, v129
	v_mov_b32_e32 v86, v129
	v_mov_b32_e32 v85, v129
	v_mov_b32_e32 v84, v129
	v_mov_b32_e32 v83, v129
	v_mov_b32_e32 v82, v129
	v_mov_b32_e32 v73, v129
	v_mov_b32_e32 v72, v129
	v_mov_b32_e32 v71, v129
	v_mov_b32_e32 v70, v129
	v_mov_b32_e32 v69, v129
	v_mov_b32_e32 v68, v129
	v_mov_b32_e32 v67, v129
	v_mov_b32_e32 v66, v129
	v_mov_b32_e32 v65, v129
	v_mov_b32_e32 v64, v129
	v_mov_b32_e32 v63, v129
	v_mov_b32_e32 v62, v129
	v_mov_b32_e32 v61, v129
	v_mov_b32_e32 v60, v129
	v_mov_b32_e32 v59, v129
	v_mov_b32_e32 v58, v129
	v_mov_b32_e32 v49, v129
	v_mov_b32_e32 v48, v129
	v_mov_b32_e32 v47, v129
	v_mov_b32_e32 v46, v129
	v_mov_b32_e32 v45, v129
	v_mov_b32_e32 v44, v129
	v_mov_b32_e32 v43, v129
	v_mov_b32_e32 v42, v129
	v_mov_b32_e32 v33, v129
	v_mov_b32_e32 v32, v129
	v_mov_b32_e32 v31, v129
	v_mov_b32_e32 v30, v129
	v_mov_b32_e32 v29, v129
	v_mov_b32_e32 v28, v129
	v_mov_b32_e32 v27, v129
	v_mov_b32_e32 v26, v129
	v_mov_b32_e32 v17, v129
	v_mov_b32_e32 v16, v129
	v_mov_b32_e32 v15, v129
	v_mov_b32_e32 v14, v129
	v_mov_b32_e32 v13, v129
	v_mov_b32_e32 v12, v129
	v_mov_b32_e32 v11, v129
	v_mov_b32_e32 v10, v129
	v_mov_b32_e32 v57, v129
	v_mov_b32_e32 v56, v129
	v_mov_b32_e32 v55, v129
	v_mov_b32_e32 v54, v129
	v_mov_b32_e32 v53, v129
	v_mov_b32_e32 v52, v129
	v_mov_b32_e32 v51, v129
	v_mov_b32_e32 v50, v129
	v_mov_b32_e32 v41, v129
	v_mov_b32_e32 v40, v129
	v_mov_b32_e32 v39, v129
	v_mov_b32_e32 v38, v129
	v_mov_b32_e32 v37, v129
	v_mov_b32_e32 v36, v129
	v_mov_b32_e32 v35, v129
	v_mov_b32_e32 v34, v129
	v_mov_b32_e32 v25, v129
	v_mov_b32_e32 v24, v129
	v_mov_b32_e32 v23, v129
	v_mov_b32_e32 v22, v129
	v_mov_b32_e32 v21, v129
	v_mov_b32_e32 v20, v129
	v_mov_b32_e32 v19, v129
	v_mov_b32_e32 v18, v129
	v_mov_b32_e32 v9, v129
	v_mov_b32_e32 v8, v129
	v_mov_b32_e32 v7, v129
	v_mov_b32_e32 v6, v129
	v_mov_b32_e32 v5, v129
	v_mov_b32_e32 v4, v129
	v_mov_b32_e32 v3, v129
	v_mov_b32_e32 v2, v129
	s_branch .LBB0_241

; template <class Epi> __device__ __forceinline__ void gemm_phase(LAS unsigned char* lds, const Gemm g, const StaticOrder& S, const Epi& E, const int tid) {
;     ...
;         const char* nA = has_next ? (const char*)g.A + (size_t)nxt.pm * tstepA + (size_t)(nxt.pn & g.amask) * g.astride : cA; const char* nB = has_next ? (const char*)g.Bt + (size_t)nxt.pn * tstepB : cB;
;         for (int t = 0; t < nt; t += 2) {
;             const bool last = (t == nt - 2);
;             const char* a1 = cA + (size_t)(t + 1) * kstep;
;             const char* a2 = last ? nA : cA + (size_t)(t + 2) * kstep; const char* b2 = last ? nB : cB + (size_t)(t + 2) * kstep;
;     ...
; #pragma unroll
;         for (int a = 0; a < 2; ++a)
; #pragma unroll
;             for (int b = 0; b < 2; ++b)
; #pragma unroll
;                 for (int m = 0; m < 4; ++m)
; #pragma unroll
;                     for (int n = 0; n < 2; ++n) acc[a][b][m][n] = (f32x4){0.f, 0.f, 0.f, 0.f};
.LBB0_544:
	s_andn2_b64 vcc, exec, s[94:95]
	s_waitcnt lgkmcnt(0)
	s_cbranch_vccnz .Lacc_clear_3
	s_add_u32 s14, s12, s18
	s_addc_u32 s15, s13, 0
	s_add_u32 s77, s12, 0x100
	s_addc_u32 vcc_lo, s13, 0
	s_add_u32 vcc_hi, s10, 0x100
	s_addc_u32 s26, s11, 0
	s_add_u32 s10, s14, 0x80
	v_mov_b64_e32 v[2:3], 0
	v_mov_b64_e32 v[4:5], 0
	v_mov_b64_e32 v[6:7], 0
	v_mov_b64_e32 v[8:9], 0
	v_mov_b64_e32 v[10:11], 0
	v_mov_b64_e32 v[12:13], 0
	v_mov_b64_e32 v[14:15], 0
	v_mov_b64_e32 v[16:17], 0
	v_mov_b64_e32 v[18:19], 0
	v_mov_b64_e32 v[20:21], 0
	v_mov_b64_e32 v[22:23], 0
	v_mov_b64_e32 v[24:25], 0
	v_mov_b64_e32 v[26:27], 0
	v_mov_b64_e32 v[28:29], 0
	v_mov_b64_e32 v[30:31], 0
	v_mov_b64_e32 v[32:33], 0
	v_mov_b64_e32 v[34:35], 0
	v_mov_b64_e32 v[36:37], 0
	v_mov_b64_e32 v[38:39], 0
	v_mov_b64_e32 v[40:41], 0
	v_mov_b64_e32 v[42:43], 0
	v_mov_b64_e32 v[44:45], 0
	v_mov_b64_e32 v[46:47], 0
	v_mov_b64_e32 v[48:49], 0
	v_mov_b64_e32 v[50:51], 0
	v_mov_b64_e32 v[52:53], 0
	v_mov_b64_e32 v[54:55], 0
	v_mov_b64_e32 v[56:57], 0
	v_mov_b64_e32 v[58:59], 0
	v_mov_b64_e32 v[60:61], 0
	v_mov_b64_e32 v[62:63], 0
	v_mov_b64_e32 v[64:65], 0
	v_mov_b64_e32 v[66:67], 0
	v_mov_b64_e32 v[68:69], 0
	v_mov_b64_e32 v[70:71], 0
	v_mov_b64_e32 v[72:73], 0
	v_mov_b64_e32 v[74:75], 0
	v_mov_b64_e32 v[76:77], 0
	v_mov_b64_e32 v[78:79], 0
	v_mov_b64_e32 v[80:81], 0
	v_mov_b64_e32 v[82:83], 0
	v_mov_b64_e32 v[84:85], 0
	v_mov_b64_e32 v[86:87], 0
	v_mov_b64_e32 v[88:89], 0
	v_mov_b64_e32 v[90:91], 0
	v_mov_b64_e32 v[92:93], 0
	v_mov_b64_e32 v[94:95], 0
	v_mov_b64_e32 v[96:97], 0
	v_mov_b64_e32 v[98:99], 0
	v_mov_b64_e32 v[100:101], 0
	v_mov_b64_e32 v[102:103], 0
	v_mov_b64_e32 v[104:105], 0
	v_mov_b64_e32 v[106:107], 0
	v_mov_b64_e32 v[108:109], 0
	v_mov_b64_e32 v[110:111], 0
	v_mov_b64_e32 v[112:113], 0
	v_mov_b64_e32 v[114:115], 0
	v_mov_b64_e32 v[116:117], 0
	v_mov_b64_e32 v[118:119], 0
	v_mov_b64_e32 v[120:121], 0
	v_mov_b64_e32 v[122:123], 0
	v_mov_b64_e32 v[124:125], 0
	v_mov_b64_e32 v[126:127], 0
	v_mov_b64_e32 v[128:129], 0
	s_addc_u32 s11, s15, 0
	s_mov_b32 s12, 0

; template <class Epi> __device__ __forceinline__ void gemm_phase(LAS unsigned char* lds, const Gemm g, const StaticOrder& S, const Epi& E, const int tid) {
;     ...
;         const char* nA = has_next ? (const char*)g.A + (size_t)nxt.pm * tstepA + (size_t)(nxt.pn & g.amask) * g.astride : cA; const char* nB = has_next ? (const char*)g.Bt + (size_t)nxt.pn * tstepB : cB;
;         for (int t = 0; t < nt; t += 2) {
;             const bool last = (t == nt - 2);
;             const char* a1 = cA + (size_t)(t + 1) * kstep;
;             const char* a2 = last ? nA : cA + (size_t)(t + 2) * kstep; const char* b2 = last ? nB : cB + (size_t)(t + 2) * kstep;
;     ...
; #pragma unroll
;         for (int a = 0; a < 2; ++a)
; #pragma unroll
;             for (int b = 0; b < 2; ++b)
; #pragma unroll
;                 for (int m = 0; m < 4; ++m)
; #pragma unroll
;                     for (int n = 0; n < 2; ++n) acc[a][b][m][n] = (f32x4){0.f, 0.f, 0.f, 0.f};
.LBB0_583:
	s_ashr_i32 s91, s90, 31
	s_lshl_b64 s[8:9], s[90:91], 20
	s_add_u32 s92, s10, s8
	s_addc_u32 s93, s11, s9
	s_ashr_i32 s89, s88, 31
	s_lshl_b64 s[8:9], s[88:89], 20
	s_add_u32 s94, s12, s8
	s_addc_u32 s95, s13, s9
	s_andn2_b64 vcc, exec, s[58:59]
	s_waitcnt lgkmcnt(0)
	s_cbranch_vccnz .Lacc_clear_4
	s_and_b64 s[8:9], s[42:43], exec
	s_cselect_b32 s36, s93, s7
	s_cselect_b32 s38, s92, s6
	s_cselect_b32 s39, s95, s5
	s_cselect_b32 s69, s94, s4
	s_add_u32 s26, s6, 0x100
	s_addc_u32 s27, s7, 0
	s_add_u32 s76, s4, 0x100
	v_mov_b64_e32 v[2:3], 0
	v_mov_b64_e32 v[4:5], 0
	v_mov_b64_e32 v[6:7], 0
	v_mov_b64_e32 v[8:9], 0
	v_mov_b64_e32 v[10:11], 0
	v_mov_b64_e32 v[12:13], 0
	v_mov_b64_e32 v[14:15], 0
	v_mov_b64_e32 v[16:17], 0
	v_mov_b64_e32 v[18:19], 0
	v_mov_b64_e32 v[20:21], 0
	v_mov_b64_e32 v[22:23], 0
	v_mov_b64_e32 v[24:25], 0
	v_mov_b64_e32 v[26:27], 0
	v_mov_b64_e32 v[28:29], 0
	v_mov_b64_e32 v[30:31], 0
	v_mov_b64_e32 v[32:33], 0
	v_mov_b64_e32 v[34:35], 0
	v_mov_b64_e32 v[36:37], 0
	v_mov_b64_e32 v[38:39], 0
	v_mov_b64_e32 v[40:41], 0
	v_mov_b64_e32 v[42:43], 0
	v_mov_b64_e32 v[44:45], 0
	v_mov_b64_e32 v[46:47], 0
	v_mov_b64_e32 v[48:49], 0
	v_mov_b64_e32 v[50:51], 0
	v_mov_b64_e32 v[52:53], 0
	v_mov_b64_e32 v[54:55], 0
	v_mov_b64_e32 v[56:57], 0
	v_mov_b64_e32 v[58:59], 0
	v_mov_b64_e32 v[60:61], 0
	v_mov_b64_e32 v[62:63], 0
	v_mov_b64_e32 v[64:65], 0
	v_mov_b64_e32 v[66:67], 0
	v_mov_b64_e32 v[68:69], 0
	v_mov_b64_e32 v[70:71], 0
	v_mov_b64_e32 v[72:73], 0
	v_mov_b64_e32 v[74:75], 0
	v_mov_b64_e32 v[76:77], 0
	v_mov_b64_e32 v[78:79], 0
	v_mov_b64_e32 v[80:81], 0
	v_mov_b64_e32 v[82:83], 0
	v_mov_b64_e32 v[84:85], 0
	v_mov_b64_e32 v[86:87], 0
	v_mov_b64_e32 v[88:89], 0
	v_mov_b64_e32 v[90:91], 0
	v_mov_b64_e32 v[92:93], 0
	v_mov_b64_e32 v[94:95], 0
	v_mov_b64_e32 v[96:97], 0
	v_mov_b64_e32 v[98:99], 0
	v_mov_b64_e32 v[100:101], 0
	v_mov_b64_e32 v[102:103], 0
	v_mov_b64_e32 v[104:105], 0
	v_mov_b64_e32 v[106:107], 0
	v_mov_b64_e32 v[108:109], 0
	v_mov_b64_e32 v[110:111], 0
	v_mov_b64_e32 v[112:113], 0
	v_mov_b64_e32 v[122:123], 0
	v_mov_b64_e32 v[124:125], 0
	v_mov_b64_e32 v[126:127], 0
	v_mov_b64_e32 v[128:129], 0
	v_mov_b64_e32 v[134:135], 0
	v_mov_b64_e32 v[136:137], 0
	v_mov_b64_e32 v[138:139], 0
	v_mov_b64_e32 v[140:141], 0
	s_addc_u32 s77, s5, 0
	s_mov_b32 s4, 0

; template <class Epi> __device__ __forceinline__ void gemm_phase(LAS unsigned char* lds, const Gemm g, const StaticOrder& S, const Epi& E, const int tid) {
;     ...
; #pragma unroll
;         for (int a = 0; a < 2; ++a)
; #pragma unroll
;             for (int b = 0; b < 2; ++b)
; #pragma unroll
;                 for (int m = 0; m < 4; ++m)
; #pragma unroll
;                     for (int n = 0; n < 2; ++n) acc[a][b][m][n] = (f32x4){0.f, 0.f, 0.f, 0.f};
.Lacc_clear_4:
	v_mov_b32_e32 v137, 0
	v_mov_b32_e32 v136, v137
	v_mov_b32_e32 v135, v137
	v_mov_b32_e32 v134, v137
	v_mov_b32_e32 v141, v137
	v_mov_b32_e32 v140, v137
	v_mov_b32_e32 v139, v137
	v_mov_b32_e32 v138, v137
	v_mov_b32_e32 v113, v137
	v_mov_b32_e32 v112, v137
	v_mov_b32_e32 v111, v137
	v_mov_b32_e32 v110, v137
	v_mov_b32_e32 v109, v137
	v_mov_b32_e32 v108, v137
	v_mov_b32_e32 v107, v137
	v_mov_b32_e32 v106, v137
	v_mov_b32_e32 v97, v137
	v_mov_b32_e32 v96, v137
	v_mov_b32_e32 v95, v137
	v_mov_b32_e32 v94, v137
	v_mov_b32_e32 v93, v137
	v_mov_b32_e32 v92, v137
	v_mov_b32_e32 v91, v137
	v_mov_b32_e32 v90, v137
	v_mov_b32_e32 v81, v137
	v_mov_b32_e32 v80, v137
	v_mov_b32_e32 v79, v137
	v_mov_b32_e32 v78, v137
	v_mov_b32_e32 v77, v137
	v_mov_b32_e32 v76, v137
	v_mov_b32_e32 v75, v137
	v_mov_b32_e32 v74, v137
	v_mov_b32_e32 v129, v137
	v_mov_b32_e32 v128, v137
	v_mov_b32_e32 v127, v137
	v_mov_b32_e32 v126, v137
	v_mov_b32_e32 v125, v137
	v_mov_b32_e32 v124, v137
	v_mov_b32_e32 v123, v137
	v_mov_b32_e32 v122, v137
	v_mov_b32_e32 v105, v137
	v_mov_b32_e32 v104, v137
	v_mov_b32_e32 v103, v137
	v_mov_b32_e32 v102, v137
	v_mov_b32_e32 v101, v137
	v_mov_b32_e32 v100, v137
	v_mov_b32_e32 v99, v137
	v_mov_b32_e32 v98, v137
	v_mov_b32_e32 v89, v137
	v_mov_b32_e32 v88, v137
	v_mov_b32_e32 v87, v137
	v_mov_b32_e32 v86, v137
	v_mov_b32_e32 v85, v137
	v_mov_b32_e32 v84, v137
	v_mov_b32_e32 v83, v137
	v_mov_b32_e32 v82, v137
	v_mov_b32_e32 v73, v137
	v_mov_b32_e32 v72, v137
	v_mov_b32_e32 v71, v137
	v_mov_b32_e32 v70, v137
	v_mov_b32_e32 v69, v137
	v_mov_b32_e32 v68, v137
	v_mov_b32_e32 v67, v137
	v_mov_b32_e32 v66, v137
	v_mov_b32_e32 v65, v137
	v_mov_b32_e32 v64, v137
	v_mov_b32_e32 v63, v137
	v_mov_b32_e32 v62, v137
	v_mov_b32_e32 v61, v137
	v_mov_b32_e32 v60, v137
	v_mov_b32_e32 v59, v137
	v_mov_b32_e32 v58, v137
	v_mov_b32_e32 v49, v137
	v_mov_b32_e32 v48, v137
	v_mov_b32_e32 v47, v137
	v_mov_b32_e32 v46, v137
	v_mov_b32_e32 v45, v137
	v_mov_b32_e32 v44, v137
	v_mov_b32_e32 v43, v137
	v_mov_b32_e32 v42, v137
	v_mov_b32_e32 v33, v137
	v_mov_b32_e32 v32, v137
	v_mov_b32_e32 v31, v137
	v_mov_b32_e32 v30, v137
	v_mov_b32_e32 v29, v137
	v_mov_b32_e32 v28, v137
	v_mov_b32_e32 v27, v137
	v_mov_b32_e32 v26, v137
	v_mov_b32_e32 v17, v137
	v_mov_b32_e32 v16, v137
	v_mov_b32_e32 v15, v137
	v_mov_b32_e32 v14, v137
	v_mov_b32_e32 v13, v137
	v_mov_b32_e32 v12, v137
	v_mov_b32_e32 v11, v137
	v_mov_b32_e32 v10, v137
	v_mov_b32_e32 v57, v137
	v_mov_b32_e32 v56, v137
	v_mov_b32_e32 v55, v137
	v_mov_b32_e32 v54, v137
	v_mov_b32_e32 v53, v137
	v_mov_b32_e32 v52, v137
	v_mov_b32_e32 v51, v137
	v_mov_b32_e32 v50, v137
	v_mov_b32_e32 v41, v137
	v_mov_b32_e32 v40, v137
	v_mov_b32_e32 v39, v137
	v_mov_b32_e32 v38, v137
	v_mov_b32_e32 v37, v137
	v_mov_b32_e32 v36, v137
	v_mov_b32_e32 v35, v137
	v_mov_b32_e32 v34, v137
	v_mov_b32_e32 v25, v137
	v_mov_b32_e32 v24, v137
	v_mov_b32_e32 v23, v137
	v_mov_b32_e32 v22, v137
	v_mov_b32_e32 v21, v137
	v_mov_b32_e32 v20, v137
	v_mov_b32_e32 v19, v137
	v_mov_b32_e32 v18, v137
	v_mov_b32_e32 v9, v137
	v_mov_b32_e32 v8, v137
	v_mov_b32_e32 v7, v137
	v_mov_b32_e32 v6, v137
	v_mov_b32_e32 v5, v137
	v_mov_b32_e32 v4, v137
	v_mov_b32_e32 v3, v137
	v_mov_b32_e32 v2, v137
	s_branch .LBB0_586

; template <class Epi> __device__ __forceinline__ void gemm_phase(LAS unsigned char* lds, const Gemm g, const StaticOrder& S, const Epi& E, const int tid) {
;     ...
;         const char* nA = has_next ? (const char*)g.A + (size_t)nxt.pm * tstepA + (size_t)(nxt.pn & g.amask) * g.astride : cA; const char* nB = has_next ? (const char*)g.Bt + (size_t)nxt.pn * tstepB : cB;
;         for (int t = 0; t < nt; t += 2) {
;             const bool last = (t == nt - 2);
;             const char* a1 = cA + (size_t)(t + 1) * kstep;
;             const char* a2 = last ? nA : cA + (size_t)(t + 2) * kstep; const char* b2 = last ? nB : cB + (size_t)(t + 2) * kstep;
;     ...
; #pragma unroll
;         for (int a = 0; a < 2; ++a)
; #pragma unroll
;             for (int b = 0; b < 2; ++b)
; #pragma unroll
;                 for (int m = 0; m < 4; ++m)
; #pragma unroll
;                     for (int n = 0; n < 2; ++n) acc[a][b][m][n] = (f32x4){0.f, 0.f, 0.f, 0.f};
.LBB0_617:
	s_ashr_i32 s89, s88, 31
	s_lshl_b64 s[8:9], s[88:89], 20
	s_add_u32 s90, s10, s8
	s_addc_u32 s91, s11, s9
	s_ashr_i32 s87, s86, 31
	s_lshl_b64 s[8:9], s[86:87], 20
	s_add_u32 s92, s12, s8
	s_addc_u32 s93, s13, s9
	s_andn2_b64 vcc, exec, s[56:57]
	s_cbranch_vccnz .Lacc_clear_5
	s_and_b64 s[8:9], s[40:41], exec
	s_cselect_b32 s38, s91, s7
	s_cselect_b32 s39, s90, s6
	s_cselect_b32 s42, s93, s5
	s_cselect_b32 s43, s92, s4
	s_add_u32 s26, s6, 0x100
	s_addc_u32 s27, s7, 0
	s_add_u32 s69, s4, 0x100
	v_mov_b64_e32 v[2:3], 0
	v_mov_b64_e32 v[4:5], 0
	v_mov_b64_e32 v[6:7], 0
	v_mov_b64_e32 v[8:9], 0
	v_mov_b64_e32 v[10:11], 0
	v_mov_b64_e32 v[12:13], 0
	v_mov_b64_e32 v[14:15], 0
	v_mov_b64_e32 v[16:17], 0
	v_mov_b64_e32 v[18:19], 0
	v_mov_b64_e32 v[20:21], 0
	v_mov_b64_e32 v[22:23], 0
	v_mov_b64_e32 v[24:25], 0
	v_mov_b64_e32 v[26:27], 0
	v_mov_b64_e32 v[28:29], 0
	v_mov_b64_e32 v[30:31], 0
	v_mov_b64_e32 v[32:33], 0
	v_mov_b64_e32 v[34:35], 0
	v_mov_b64_e32 v[36:37], 0
	v_mov_b64_e32 v[38:39], 0
	v_mov_b64_e32 v[40:41], 0
	v_mov_b64_e32 v[42:43], 0
	v_mov_b64_e32 v[44:45], 0
	v_mov_b64_e32 v[46:47], 0
	v_mov_b64_e32 v[48:49], 0
	v_mov_b64_e32 v[50:51], 0
	v_mov_b64_e32 v[52:53], 0
	v_mov_b64_e32 v[54:55], 0
	v_mov_b64_e32 v[56:57], 0
	v_mov_b64_e32 v[58:59], 0
	v_mov_b64_e32 v[60:61], 0
	v_mov_b64_e32 v[62:63], 0
	v_mov_b64_e32 v[64:65], 0
	v_mov_b64_e32 v[66:67], 0
	v_mov_b64_e32 v[68:69], 0
	v_mov_b64_e32 v[70:71], 0
	v_mov_b64_e32 v[72:73], 0
	v_mov_b64_e32 v[74:75], 0
	v_mov_b64_e32 v[76:77], 0
	v_mov_b64_e32 v[78:79], 0
	v_mov_b64_e32 v[80:81], 0
	v_mov_b64_e32 v[82:83], 0
	v_mov_b64_e32 v[84:85], 0
	v_mov_b64_e32 v[86:87], 0
	v_mov_b64_e32 v[88:89], 0
	v_mov_b64_e32 v[90:91], 0
	v_mov_b64_e32 v[92:93], 0
	v_mov_b64_e32 v[94:95], 0
	v_mov_b64_e32 v[96:97], 0
	v_mov_b64_e32 v[98:99], 0
	v_mov_b64_e32 v[100:101], 0
	v_mov_b64_e32 v[102:103], 0
	v_mov_b64_e32 v[104:105], 0
	v_mov_b64_e32 v[106:107], 0
	v_mov_b64_e32 v[108:109], 0
	v_mov_b64_e32 v[110:111], 0
	v_mov_b64_e32 v[112:113], 0
	v_mov_b64_e32 v[114:115], 0
	v_mov_b64_e32 v[116:117], 0
	v_mov_b64_e32 v[118:119], 0
	v_mov_b64_e32 v[120:121], 0
	v_mov_b64_e32 v[122:123], 0
	v_mov_b64_e32 v[124:125], 0
	v_mov_b64_e32 v[126:127], 0
	v_mov_b64_e32 v[128:129], 0
	s_addc_u32 s76, s5, 0
	s_mov_b32 s4, 0

; template <class Epi> __device__ __forceinline__ void gemm_phase(LAS unsigned char* lds, const Gemm g, const StaticOrder& S, const Epi& E, const int tid) {
;     ...
; #pragma unroll
;         for (int a = 0; a < 2; ++a)
; #pragma unroll
;             for (int b = 0; b < 2; ++b)
; #pragma unroll
;                 for (int m = 0; m < 4; ++m)
; #pragma unroll
;                     for (int n = 0; n < 2; ++n) acc[a][b][m][n] = (f32x4){0.f, 0.f, 0.f, 0.f};
.Lacc_clear_5:
	v_mov_b32_e32 v125, 0
	v_mov_b32_e32 v124, v125
	v_mov_b32_e32 v123, v125
	v_mov_b32_e32 v122, v125
	v_mov_b32_e32 v121, v125
	v_mov_b32_e32 v120, v125
	v_mov_b32_e32 v119, v125
	v_mov_b32_e32 v118, v125
	v_mov_b32_e32 v113, v125
	v_mov_b32_e32 v112, v125
	v_mov_b32_e32 v111, v125
	v_mov_b32_e32 v110, v125
	v_mov_b32_e32 v105, v125
	v_mov_b32_e32 v104, v125
	v_mov_b32_e32 v103, v125
	v_mov_b32_e32 v102, v125
	v_mov_b32_e32 v97, v125
	v_mov_b32_e32 v96, v125
	v_mov_b32_e32 v95, v125
	v_mov_b32_e32 v94, v125
	v_mov_b32_e32 v89, v125
	v_mov_b32_e32 v88, v125
	v_mov_b32_e32 v87, v125
	v_mov_b32_e32 v86, v125
	v_mov_b32_e32 v81, v125
	v_mov_b32_e32 v80, v125
	v_mov_b32_e32 v79, v125
	v_mov_b32_e32 v78, v125
	v_mov_b32_e32 v73, v125
	v_mov_b32_e32 v72, v125
	v_mov_b32_e32 v71, v125
	v_mov_b32_e32 v70, v125
	v_mov_b32_e32 v129, v125
	v_mov_b32_e32 v128, v125
	v_mov_b32_e32 v127, v125
	v_mov_b32_e32 v126, v125
	v_mov_b32_e32 v117, v125
	v_mov_b32_e32 v116, v125
	v_mov_b32_e32 v115, v125
	v_mov_b32_e32 v114, v125
	v_mov_b32_e32 v109, v125
	v_mov_b32_e32 v108, v125
	v_mov_b32_e32 v107, v125
	v_mov_b32_e32 v106, v125
	v_mov_b32_e32 v101, v125
	v_mov_b32_e32 v100, v125
	v_mov_b32_e32 v99, v125
	v_mov_b32_e32 v98, v125
	v_mov_b32_e32 v93, v125
	v_mov_b32_e32 v92, v125
	v_mov_b32_e32 v91, v125
	v_mov_b32_e32 v90, v125
	v_mov_b32_e32 v85, v125
	v_mov_b32_e32 v84, v125
	v_mov_b32_e32 v83, v125
	v_mov_b32_e32 v82, v125
	v_mov_b32_e32 v77, v125
	v_mov_b32_e32 v76, v125
	v_mov_b32_e32 v75, v125
	v_mov_b32_e32 v74, v125
	v_mov_b32_e32 v69, v125
	v_mov_b32_e32 v68, v125
	v_mov_b32_e32 v67, v125
	v_mov_b32_e32 v66, v125
	v_mov_b32_e32 v65, v125
	v_mov_b32_e32 v64, v125
	v_mov_b32_e32 v63, v125
	v_mov_b32_e32 v62, v125
	v_mov_b32_e32 v57, v125
	v_mov_b32_e32 v56, v125
	v_mov_b32_e32 v55, v125
	v_mov_b32_e32 v54, v125
	v_mov_b32_e32 v49, v125
	v_mov_b32_e32 v48, v125
	v_mov_b32_e32 v47, v125
	v_mov_b32_e32 v46, v125
	v_mov_b32_e32 v41, v125
	v_mov_b32_e32 v40, v125
	v_mov_b32_e32 v39, v125
	v_mov_b32_e32 v38, v125
	v_mov_b32_e32 v33, v125
	v_mov_b32_e32 v32, v125
	v_mov_b32_e32 v31, v125
	v_mov_b32_e32 v30, v125
	v_mov_b32_e32 v25, v125
	v_mov_b32_e32 v24, v125
	v_mov_b32_e32 v23, v125
	v_mov_b32_e32 v22, v125
	v_mov_b32_e32 v17, v125
	v_mov_b32_e32 v16, v125
	v_mov_b32_e32 v15, v125
	v_mov_b32_e32 v14, v125
	v_mov_b32_e32 v9, v125
	v_mov_b32_e32 v8, v125
	v_mov_b32_e32 v7, v125
	v_mov_b32_e32 v6, v125
	v_mov_b32_e32 v61, v125
	v_mov_b32_e32 v60, v125
	v_mov_b32_e32 v59, v125
	v_mov_b32_e32 v58, v125
	v_mov_b32_e32 v53, v125
	v_mov_b32_e32 v52, v125
	v_mov_b32_e32 v51, v125
	v_mov_b32_e32 v50, v125
	v_mov_b32_e32 v45, v125
	v_mov_b32_e32 v44, v125
	v_mov_b32_e32 v43, v125
	v_mov_b32_e32 v42, v125
	v_mov_b32_e32 v37, v125
	v_mov_b32_e32 v36, v125
	v_mov_b32_e32 v35, v125
	v_mov_b32_e32 v34, v125
	v_mov_b32_e32 v29, v125
	v_mov_b32_e32 v28, v125
	v_mov_b32_e32 v27, v125
	v_mov_b32_e32 v26, v125
	v_mov_b32_e32 v21, v125
	v_mov_b32_e32 v20, v125
	v_mov_b32_e32 v19, v125
	v_mov_b32_e32 v18, v125
	v_mov_b32_e32 v13, v125
	v_mov_b32_e32 v12, v125
	v_mov_b32_e32 v11, v125
	v_mov_b32_e32 v10, v125
	v_mov_b32_e32 v5, v125
	v_mov_b32_e32 v4, v125
	v_mov_b32_e32 v3, v125
	v_mov_b32_e32 v2, v125
	s_branch .LBB0_620
